# all stores write-through (sc1); L2 writeback dropped from the grid barrier
# baseline (speedup 1.0000x reference)
.LBB0_42:
	v_ashrrev_i32_e32 v13, 31, v4
	v_mov_b32_e32 v12, v4
	v_ashrrev_i32_e32 v11, 31, v5
	v_mov_b32_e32 v10, v5
	v_lshl_add_u64 v[14:15], v[12:13], 2, s[22:23]
	v_lshl_add_u64 v[16:17], v[10:11], 2, s[22:23]
	global_load_dword v3, v[14:15], off
	global_load_dword v18, v[16:17], off
	v_lshrrev_b32_e32 v15, 13, v4
	v_lshrrev_b32_e32 v17, 6, v4
	v_add_u32_e32 v9, -2, v9
	v_lshrrev_b32_e32 v14, 13, v5
	v_lshrrev_b32_e32 v16, 6, v5
	v_and_b32_e32 v15, 1, v15
	v_and_b32_e32 v17, 1, v17
	v_cmp_eq_u32_e32 vcc, 0, v9
	v_and_b32_e32 v14, 1, v14
	v_and_b32_e32 v16, 1, v16
	s_or_b64 s[30:31], vcc, s[30:31]
	v_cmp_le_u32_e32 vcc, v17, v15
	v_cmp_le_u32_e64 s[4:5], v16, v14
	v_add_u32_e32 v5, s17, v5
	v_add_u32_e32 v4, s3, v4
	v_lshl_add_u64 v[12:13], v[12:13], 1, s[28:29]
	v_lshl_add_u64 v[10:11], v[10:11], 1, s[28:29]
	s_waitcnt vmcnt(1)
	v_cndmask_b32_e32 v3, 0, v3, vcc
	s_waitcnt vmcnt(0)
	v_cndmask_b32_e64 v14, 0, v18, s[4:5]
	v_and_b32_sdwa v16, v3, v8 dst_sel:DWORD dst_unused:UNUSED_PAD src0_sel:WORD_1 src1_sel:DWORD
	v_and_b32_sdwa v15, v14, v8 dst_sel:DWORD dst_unused:UNUSED_PAD src0_sel:WORD_1 src1_sel:DWORD
	v_add3_u32 v3, v3, v16, s19
	v_add3_u32 v14, v14, v15, s19
	global_store_short_d16_hi v[12:13], v3, off sc1
	global_store_short_d16_hi v[10:11], v14, off sc1
	s_andn2_b64 exec, exec, s[30:31]
	s_cbranch_execnz .LBB0_42
	s_or_b64 exec, exec, s[30:31]
	v_mad_u64_u32 v[2:3], s[4:5], v7, s24, v[2:3]
	v_cmp_ne_u32_e32 vcc, v6, v7
	s_orn2_b64 s[4:5], vcc, exec

.LBB0_46:
	global_load_dword v3, v[4:5], off
	v_bfe_u32 v8, v2, 13, 1
	v_bfe_u32 v9, v2, 6, 1
	v_cmp_le_u32_e32 vcc, v9, v8
	v_add_u32_e32 v2, s24, v2
	v_cmp_lt_i32_e64 s[4:5], s17, v2
	v_lshl_add_u64 v[4:5], v[4:5], 0, s[22:23]
	s_or_b64 s[28:29], s[4:5], s[28:29]
	s_waitcnt vmcnt(0)
	v_cndmask_b32_e32 v3, 0, v3, vcc
	v_bfe_u32 v8, v3, 16, 1
	v_add3_u32 v3, v3, v8, s3
	global_store_short_d16_hi v[6:7], v3, off sc1
	v_lshl_add_u64 v[6:7], v[6:7], 0, s[26:27]
	s_andn2_b64 exec, exec, s[28:29]
	s_cbranch_execnz .LBB0_46

.LBB0_49:
	global_load_dwordx4 v[20:23], v[8:9], off offset:-3072
	global_load_dwordx4 v[24:27], v[8:9], off offset:-2048
	global_load_dwordx4 v[0:3], v[8:9], off
	global_load_dwordx4 v[28:31], v[8:9], off offset:-1024
	global_load_dwordx4 v[32:35], v[4:5], off
	s_add_i32 s16, s16, s18
	v_lshl_add_u64 v[8:9], v[8:9], 0, s[8:9]
	s_cmpk_lt_i32 s16, 0x4000
	s_waitcnt vmcnt(4)
	v_pk_mul_f32 v[36:37], v[22:23], v[22:23]
	v_pk_mul_f32 v[38:39], v[20:21], v[20:21]
	s_waitcnt vmcnt(3)
	v_pk_mul_f32 v[40:41], v[26:27], v[26:27]
	v_pk_mul_f32 v[42:43], v[24:25], v[24:25]
	v_mov_b32_e32 v48, v20
	v_mov_b32_e32 v49, v22
	s_waitcnt vmcnt(0)
	v_mov_b32_e32 v50, v32
	v_mov_b32_e32 v51, v34
	v_mov_b32_e32 v22, v21
	v_mov_b32_e32 v34, v33
	v_pk_mov_b32 v[20:21], v[38:39], v[36:37] op_sel:[1,0]
	v_mov_b32_e32 v39, v37
	v_pk_mov_b32 v[32:33], v[42:43], v[40:41] op_sel:[1,0]
	v_mov_b32_e32 v43, v41
	v_mul_f32_e32 v45, v1, v1
	v_mul_f32_e32 v47, v2, v2
	v_mul_f32_e32 v44, v29, v29
	v_mul_f32_e32 v46, v31, v31
	v_pk_add_f32 v[20:21], v[20:21], v[38:39]
	v_pk_add_f32 v[32:33], v[32:33], v[42:43]
	v_mul_f32_e32 v19, v0, v0
	v_mul_f32_e32 v52, v3, v3
	v_pk_fma_f32 v[36:37], v[28:29], v[28:29], v[44:45] op_sel_hi:[1,1,0]
	v_pk_fma_f32 v[40:41], v[30:31], v[30:31], v[46:47] op_sel_hi:[1,1,0]
	v_pk_add_f32 v[20:21], v[20:21], v[20:21] op_sel:[0,1] op_sel_hi:[1,0]
	v_pk_add_f32 v[32:33], v[32:33], v[32:33] op_sel:[0,1] op_sel_hi:[1,0]
	v_mov_b32_e32 v37, v47
	v_mov_b32_e32 v41, v52
	v_mov_b32_e32 v21, v19
	v_mov_b32_e32 v33, v45
	v_pk_add_f32 v[36:37], v[36:37], v[40:41]
	v_pk_add_f32 v[20:21], v[20:21], v[32:33]
	s_nop 0
	v_pk_add_f32 v[20:21], v[20:21], v[36:37]
	s_nop 0
	v_add_f32_e32 v19, v20, v21
	ds_bpermute_b32 v20, v10, v19
	s_waitcnt lgkmcnt(0)
	v_add_f32_e32 v19, v19, v20
	ds_bpermute_b32 v20, v11, v19
	s_waitcnt lgkmcnt(0)
	v_add_f32_e32 v19, v19, v20
	ds_bpermute_b32 v20, v12, v19
	s_waitcnt lgkmcnt(0)
	v_add_f32_e32 v19, v19, v20
	ds_bpermute_b32 v20, v13, v19
	s_waitcnt lgkmcnt(0)
	v_add_f32_e32 v19, v19, v20
	ds_bpermute_b32 v20, v14, v19
	s_waitcnt lgkmcnt(0)
	v_add_f32_e32 v19, v19, v20
	ds_bpermute_b32 v20, v15, v19
	s_waitcnt lgkmcnt(0)
	v_add_f32_e32 v19, v19, v20
	v_fmamk_f32 v19, v19, 0x3a800000, v16
	v_mul_f32_e32 v20, 0x4f800000, v19
	v_cmp_gt_f32_e32 vcc, s3, v19
	s_nop 1
	v_cndmask_b32_e32 v19, v19, v20, vcc
	v_sqrt_f32_e32 v20, v19
	s_nop 0
	v_add_u32_e32 v21, -1, v20
	v_add_u32_e32 v32, 1, v20
	v_fma_f32 v33, -v21, v20, v19
	v_fma_f32 v36, -v32, v20, v19
	v_cmp_ge_f32_e64 s[4:5], 0, v33
	s_nop 1
	v_cndmask_b32_e64 v20, v20, v21, s[4:5]
	v_cmp_lt_f32_e64 s[4:5], 0, v36
	s_nop 1
	v_cndmask_b32_e64 v20, v20, v32, s[4:5]
	v_mul_f32_e32 v21, 0x37800000, v20
	v_cndmask_b32_e32 v20, v20, v21, vcc
	v_cmp_class_f32_e32 vcc, v19, v17
	s_nop 1
	v_cndmask_b32_e32 v19, v20, v19, vcc
	v_div_scale_f32 v20, s[4:5], v19, v19, 1.0
	v_rcp_f32_e32 v32, v20
	v_div_scale_f32 v21, vcc, 1.0, v19, 1.0
	v_fma_f32 v33, -v20, v32, 1.0
	v_fmac_f32_e32 v32, v33, v32
	v_mul_f32_e32 v33, v21, v32
	v_fma_f32 v36, -v20, v33, v21
	v_fmac_f32_e32 v33, v36, v32
	v_fma_f32 v20, -v20, v33, v21
	v_div_fmas_f32 v20, v20, v32, v33
	v_div_fixup_f32 v32, v20, v19, 1.0
	v_pk_mul_f32 v[20:21], v[48:49], v[32:33] op_sel_hi:[1,0]
	v_pk_mul_f32 v[22:23], v[22:23], v[32:33] op_sel_hi:[1,0]
	v_pk_mul_f32 v[20:21], v[50:51], v[20:21]
	v_pk_mul_f32 v[22:23], v[34:35], v[22:23]
	v_and_b32_sdwa v19, v21, v18 dst_sel:DWORD dst_unused:UNUSED_PAD src0_sel:WORD_1 src1_sel:DWORD
	v_and_b32_sdwa v34, v23, v18 dst_sel:DWORD dst_unused:UNUSED_PAD src0_sel:WORD_1 src1_sel:DWORD
	v_and_b32_sdwa v35, v22, v18 dst_sel:DWORD dst_unused:UNUSED_PAD src0_sel:WORD_1 src1_sel:DWORD
	v_and_b32_sdwa v33, v20, v18 dst_sel:DWORD dst_unused:UNUSED_PAD src0_sel:WORD_1 src1_sel:DWORD
	v_add3_u32 v19, v21, v19, s10
	v_add3_u32 v21, v23, v34, s10
	v_add3_u32 v22, v22, v35, s10
	v_add3_u32 v20, v20, v33, s10
	v_and_b32_e32 v21, 0xffff0000, v21
	v_and_b32_e32 v22, 0xffff0000, v22
	v_or_b32_sdwa v21, v21, v19 dst_sel:DWORD dst_unused:UNUSED_PAD src0_sel:DWORD src1_sel:WORD_1
	v_or_b32_sdwa v20, v22, v20 dst_sel:DWORD dst_unused:UNUSED_PAD src0_sel:DWORD src1_sel:WORD_1
	global_store_dwordx2 v[6:7], v[20:21], off sc1
	global_load_dwordx4 v[20:23], v[4:5], off offset:1024
	v_mov_b32_e32 v34, v24
	v_mov_b32_e32 v35, v26
	v_mov_b32_e32 v26, v25
	v_pk_mul_f32 v[24:25], v[34:35], v[32:33] op_sel_hi:[1,0]
	v_pk_mul_f32 v[26:27], v[26:27], v[32:33] op_sel_hi:[1,0]
	s_waitcnt vmcnt(0)
	v_mov_b32_e32 v34, v20
	v_mov_b32_e32 v35, v22
	v_mov_b32_e32 v22, v21
	v_pk_mul_f32 v[20:21], v[34:35], v[24:25]
	v_pk_mul_f32 v[22:23], v[22:23], v[26:27]
	v_and_b32_sdwa v19, v21, v18 dst_sel:DWORD dst_unused:UNUSED_PAD src0_sel:WORD_1 src1_sel:DWORD
	v_and_b32_sdwa v25, v23, v18 dst_sel:DWORD dst_unused:UNUSED_PAD src0_sel:WORD_1 src1_sel:DWORD
	v_and_b32_sdwa v26, v22, v18 dst_sel:DWORD dst_unused:UNUSED_PAD src0_sel:WORD_1 src1_sel:DWORD
	v_and_b32_sdwa v24, v20, v18 dst_sel:DWORD dst_unused:UNUSED_PAD src0_sel:WORD_1 src1_sel:DWORD
	v_add3_u32 v19, v21, v19, s10
	v_add3_u32 v21, v23, v25, s10
	v_add3_u32 v22, v22, v26, s10
	v_add3_u32 v20, v20, v24, s10
	v_and_b32_e32 v21, 0xffff0000, v21
	v_and_b32_e32 v22, 0xffff0000, v22
	v_or_b32_sdwa v21, v21, v19 dst_sel:DWORD dst_unused:UNUSED_PAD src0_sel:DWORD src1_sel:WORD_1
	v_or_b32_sdwa v20, v22, v20 dst_sel:DWORD dst_unused:UNUSED_PAD src0_sel:DWORD src1_sel:WORD_1
	global_store_dwordx2 v[6:7], v[20:21], off offset:512 sc1
	global_load_dwordx4 v[20:23], v[4:5], off offset:2048
	v_mov_b32_e32 v24, v28
	v_mov_b32_e32 v25, v30
	v_mov_b32_e32 v30, v29
	v_pk_mul_f32 v[24:25], v[24:25], v[32:33] op_sel_hi:[1,0]
	v_pk_mul_f32 v[26:27], v[30:31], v[32:33] op_sel_hi:[1,0]
	s_waitcnt vmcnt(0)
	v_mov_b32_e32 v28, v20
	v_mov_b32_e32 v29, v22
	v_mov_b32_e32 v22, v21
	v_pk_mul_f32 v[20:21], v[28:29], v[24:25]
	v_pk_mul_f32 v[22:23], v[22:23], v[26:27]
	v_and_b32_sdwa v19, v21, v18 dst_sel:DWORD dst_unused:UNUSED_PAD src0_sel:WORD_1 src1_sel:DWORD
	v_and_b32_sdwa v25, v23, v18 dst_sel:DWORD dst_unused:UNUSED_PAD src0_sel:WORD_1 src1_sel:DWORD
	v_and_b32_sdwa v26, v22, v18 dst_sel:DWORD dst_unused:UNUSED_PAD src0_sel:WORD_1 src1_sel:DWORD
	v_and_b32_sdwa v24, v20, v18 dst_sel:DWORD dst_unused:UNUSED_PAD src0_sel:WORD_1 src1_sel:DWORD
	v_add3_u32 v19, v21, v19, s10
	v_add3_u32 v21, v23, v25, s10
	v_add3_u32 v22, v22, v26, s10
	v_add3_u32 v20, v20, v24, s10
	v_and_b32_e32 v21, 0xffff0000, v21
	v_and_b32_e32 v22, 0xffff0000, v22
	v_or_b32_sdwa v21, v21, v19 dst_sel:DWORD dst_unused:UNUSED_PAD src0_sel:DWORD src1_sel:WORD_1
	v_or_b32_sdwa v20, v22, v20 dst_sel:DWORD dst_unused:UNUSED_PAD src0_sel:DWORD src1_sel:WORD_1
	global_store_dwordx2 v[6:7], v[20:21], off offset:1024 sc1
	global_load_dwordx4 v[20:23], v[4:5], off offset:3072
	v_mov_b32_e32 v24, v0
	v_mov_b32_e32 v25, v2
	v_mov_b32_e32 v2, v1
	v_pk_mul_f32 v[0:1], v[24:25], v[32:33] op_sel_hi:[1,0]
	v_pk_mul_f32 v[2:3], v[2:3], v[32:33] op_sel_hi:[1,0]
	s_waitcnt vmcnt(0)
	v_mov_b32_e32 v25, v22
	v_mov_b32_e32 v22, v21
	v_mov_b32_e32 v24, v20
	v_pk_mul_f32 v[2:3], v[22:23], v[2:3]
	v_pk_mul_f32 v[0:1], v[24:25], v[0:1]
	v_and_b32_sdwa v21, v3, v18 dst_sel:DWORD dst_unused:UNUSED_PAD src0_sel:WORD_1 src1_sel:DWORD
	v_and_b32_sdwa v22, v2, v18 dst_sel:DWORD dst_unused:UNUSED_PAD src0_sel:WORD_1 src1_sel:DWORD
	v_and_b32_sdwa v19, v1, v18 dst_sel:DWORD dst_unused:UNUSED_PAD src0_sel:WORD_1 src1_sel:DWORD
	v_and_b32_sdwa v20, v0, v18 dst_sel:DWORD dst_unused:UNUSED_PAD src0_sel:WORD_1 src1_sel:DWORD
	v_add3_u32 v3, v3, v21, s10
	v_add3_u32 v2, v2, v22, s10
	v_add3_u32 v0, v0, v20, s10
	v_add3_u32 v1, v1, v19, s10
	v_and_b32_e32 v3, 0xffff0000, v3
	v_and_b32_e32 v2, 0xffff0000, v2
	v_or_b32_sdwa v1, v3, v1 dst_sel:DWORD dst_unused:UNUSED_PAD src0_sel:DWORD src1_sel:WORD_1
	v_or_b32_sdwa v0, v2, v0 dst_sel:DWORD dst_unused:UNUSED_PAD src0_sel:DWORD src1_sel:WORD_1
	global_store_dwordx2 v[6:7], v[0:1], off offset:1536 sc1
	v_lshl_add_u64 v[6:7], v[6:7], 0, s[6:7]
	s_cbranch_scc1 .LBB0_49

.LBB0_84:
	s_andn2_saveexec_b64 s[6:7], s[6:7]
	s_cbranch_execz .LBB0_102
	s_mov_b64 s[6:7], exec
	s_waitcnt lgkmcnt(0)
	s_waitcnt vmcnt(0)
	v_mbcnt_lo_u32_b32 v1, s6, 0
	v_mbcnt_hi_u32_b32 v1, s7, v1
	v_cmp_eq_u32_e32 vcc, 0, v1
	s_and_saveexec_b64 s[8:9], vcc
	s_cbranch_execz .LBB0_87
	s_bcnt1_i32_b64 s3, s[6:7]
	v_mov_b32_e32 v2, 0x2e03000
	v_mov_b32_e32 v3, s3
	global_atomic_add v2, v2, v3, s[0:1] offset:1024 sc0

.LBB0_177:
	s_mov_b32 s81, s80
	s_mov_b32 s50, s80
	s_mov_b32 s51, s80
	s_lshl_b32 s73, s71, 2
	v_pk_mul_f32 v[138:139], s[50:51], v[138:139]
	v_pk_mul_f32 v[136:137], s[80:81], v[136:137]
	s_and_b64 vcc, exec, s[46:47]
	v_pk_mul_f32 v[144:145], s[50:51], v[144:145]
	v_pk_mul_f32 v[142:143], s[80:81], v[142:143]
	v_cvt_pk_bf16_f32 v136, v136, v137
	v_cvt_pk_bf16_f32 v137, v138, v139
	s_nop 0
	v_cvt_pk_bf16_f32 v138, v142, v143
	v_cvt_pk_bf16_f32 v139, v144, v145
	global_store_dwordx4 v[134:135], v[136:139], off offset:256 sc1
	s_cbranch_vccnz .LBB0_181
	v_and_b32_e32 v134, 64, v230
	v_xor_b32_e32 v0, 16, v230
	v_add_u32_e32 v136, 64, v134
	v_cmp_lt_i32_e32 vcc, v0, v136
	s_nop 1
	v_cndmask_b32_e32 v0, v230, v0, vcc
	v_lshlrev_b32_e32 v0, 2, v0
	ds_bpermute_b32 v134, v0, v132
	ds_bpermute_b32 v135, v0, v133
	v_xor_b32_e32 v0, 32, v230
	v_cmp_lt_i32_e32 vcc, v0, v136
	s_waitcnt lgkmcnt(0)
	v_pk_add_f32 v[132:133], v[132:133], v[134:135]
	v_cndmask_b32_e32 v0, v230, v0, vcc
	v_lshlrev_b32_e32 v0, 2, v0
	ds_bpermute_b32 v134, v0, v132
	ds_bpermute_b32 v135, v0, v133
	s_and_saveexec_b64 s[50:51], s[38:39]
	s_cbranch_execz .LBB0_180
	s_waitcnt lgkmcnt(0)
	v_pk_add_f32 v[132:133], v[132:133], v[134:135]
	v_lshlrev_b64 v[134:135], 6, v[140:141]
	v_lshl_add_u64 v[134:135], s[66:67], 0, v[134:135]
	s_lshl_b32 s30, s73, 3
	v_lshl_add_u64 v[134:135], v[134:135], 0, s[30:31]
	s_lshl_b32 s30, s16, 3
	v_lshl_add_u64 v[134:135], v[134:135], 0, s[30:31]
	global_store_dwordx2 v[134:135], v[132:133], off sc1

.LBB0_196:
	s_mov_b32 s50, s80
	s_mov_b32 s51, s80
	v_pk_mul_f32 v[150:151], s[50:51], v[144:145]
	v_pk_mul_f32 v[144:145], s[80:81], v[146:147]
	s_and_b64 vcc, exec, s[46:47]
	v_pk_mul_f32 v[148:149], s[50:51], v[142:143]
	v_pk_mul_f32 v[138:139], s[80:81], v[138:139]
	s_nop 0
	v_cvt_pk_bf16_f32 v142, v138, v139
	v_cvt_pk_bf16_f32 v143, v148, v149
	v_cvt_pk_bf16_f32 v144, v144, v145
	v_cvt_pk_bf16_f32 v145, v150, v151
	global_store_dwordx4 v[136:137], v[142:145], off offset:256 sc1
	s_cbranch_vccnz .LBB0_200
	v_and_b32_e32 v136, 64, v230
	v_xor_b32_e32 v0, 16, v230
	v_add_u32_e32 v138, 64, v136
	v_cmp_lt_i32_e32 vcc, v0, v138
	s_nop 1
	v_cndmask_b32_e32 v0, v230, v0, vcc
	v_lshlrev_b32_e32 v0, 2, v0
	ds_bpermute_b32 v136, v0, v132
	ds_bpermute_b32 v137, v0, v133
	v_xor_b32_e32 v0, 32, v230
	v_cmp_lt_i32_e32 vcc, v0, v138
	s_waitcnt lgkmcnt(0)
	v_pk_add_f32 v[132:133], v[132:133], v[136:137]
	v_cndmask_b32_e32 v0, v230, v0, vcc
	v_lshlrev_b32_e32 v0, 2, v0
	ds_bpermute_b32 v136, v0, v132
	ds_bpermute_b32 v137, v0, v133
	s_and_saveexec_b64 s[50:51], s[38:39]
	s_cbranch_execz .LBB0_199
	v_lshlrev_b64 v[134:135], 6, v[134:135]
	v_lshl_add_u64 v[134:135], s[66:67], 0, v[134:135]
	s_lshl_b32 s30, s73, 3
	v_lshl_add_u64 v[134:135], v[134:135], 0, s[30:31]
	s_lshl_b32 s30, s16, 3
	s_waitcnt lgkmcnt(0)
	v_pk_add_f32 v[132:133], v[132:133], v[136:137]
	v_lshl_add_u64 v[134:135], v[134:135], 0, s[30:31]
	global_store_dwordx2 v[134:135], v[132:133], off sc1

.LBB0_256:
	s_mov_b32 s84, s80
	s_mov_b32 s85, s80
	v_pk_mul_f32 v[134:135], s[84:85], v[134:135]
	v_pk_mul_f32 v[132:133], s[80:81], v[132:133]
	s_and_b64 vcc, exec, s[46:47]
	v_pk_mul_f32 v[138:139], s[84:85], v[138:139]
	v_pk_mul_f32 v[136:137], s[80:81], v[136:137]
	v_cvt_pk_bf16_f32 v132, v132, v133
	v_cvt_pk_bf16_f32 v133, v134, v135
	s_nop 0
	v_cvt_pk_bf16_f32 v134, v136, v137
	v_cvt_pk_bf16_f32 v135, v138, v139
	global_store_dwordx4 v[146:147], v[132:135], off offset:256 sc1
	s_cbranch_vccnz .LBB0_260
	s_nop 0
	v_and_b32_e32 v132, 64, v230
	v_xor_b32_e32 v0, 16, v230
	v_add_u32_e32 v134, 64, v132
	v_cmp_lt_i32_e32 vcc, v0, v134
	s_nop 1
	v_cndmask_b32_e32 v0, v230, v0, vcc
	v_lshlrev_b32_e32 v0, 2, v0
	ds_bpermute_b32 v132, v0, v142
	ds_bpermute_b32 v133, v0, v143
	v_xor_b32_e32 v0, 32, v230
	v_cmp_lt_i32_e32 vcc, v0, v134
	s_waitcnt lgkmcnt(0)
	v_pk_add_f32 v[132:133], v[142:143], v[132:133]
	v_cndmask_b32_e32 v0, v230, v0, vcc
	v_lshlrev_b32_e32 v0, 2, v0
	ds_bpermute_b32 v134, v0, v132
	ds_bpermute_b32 v135, v0, v133
	s_and_saveexec_b64 s[84:85], s[38:39]
	s_cbranch_execz .LBB0_259
	s_waitcnt lgkmcnt(0)
	v_pk_add_f32 v[132:133], v[132:133], v[134:135]
	v_lshlrev_b64 v[134:135], 6, v[144:145]
	v_lshl_add_u64 v[134:135], s[66:67], 0, v[134:135]
	s_lshl_b32 s30, s73, 3
	v_lshl_add_u64 v[134:135], v[134:135], 0, s[30:31]
	s_lshl_b32 s30, s16, 3
	v_lshl_add_u64 v[134:135], v[134:135], 0, s[30:31]
	global_store_dwordx2 v[134:135], v[132:133], off sc1

.LBB0_319:
	s_mov_b32 s48, s80
	s_mov_b32 s49, s80
	v_pk_mul_f32 v[134:135], s[48:49], v[134:135]
	v_pk_mul_f32 v[132:133], s[80:81], v[132:133]
	s_and_b64 vcc, exec, s[46:47]
	v_pk_mul_f32 v[138:139], s[48:49], v[138:139]
	v_pk_mul_f32 v[136:137], s[80:81], v[136:137]
	v_cvt_pk_bf16_f32 v132, v132, v133
	v_cvt_pk_bf16_f32 v133, v134, v135
	s_nop 0
	v_cvt_pk_bf16_f32 v134, v136, v137
	v_cvt_pk_bf16_f32 v135, v138, v139
	global_store_dwordx4 v[2:3], v[132:135], off offset:256 sc1
	s_cbranch_vccnz .LBB0_323
	v_and_b32_e32 v2, 64, v230
	v_xor_b32_e32 v0, 16, v230
	v_add_u32_e32 v132, 64, v2
	v_cmp_lt_i32_e32 vcc, v0, v132
	s_nop 1
	v_cndmask_b32_e32 v0, v230, v0, vcc
	v_lshlrev_b32_e32 v0, 2, v0
	ds_bpermute_b32 v2, v0, v142
	ds_bpermute_b32 v3, v0, v143
	v_xor_b32_e32 v0, 32, v230
	v_cmp_lt_i32_e32 vcc, v0, v132
	s_waitcnt lgkmcnt(0)
	v_pk_add_f32 v[2:3], v[142:143], v[2:3]
	v_cndmask_b32_e32 v0, v230, v0, vcc
	v_lshlrev_b32_e32 v0, 2, v0
	ds_bpermute_b32 v132, v0, v2
	ds_bpermute_b32 v133, v0, v3
	s_and_saveexec_b64 s[46:47], s[38:39]
	s_cbranch_execz .LBB0_322
	s_waitcnt lgkmcnt(0)
	v_pk_add_f32 v[2:3], v[2:3], v[132:133]
	v_lshlrev_b64 v[132:133], 6, v[140:141]
	v_lshl_add_u64 v[132:133], s[66:67], 0, v[132:133]
	s_lshl_b32 s30, s73, 3
	v_lshl_add_u64 v[132:133], v[132:133], 0, s[30:31]
	s_lshl_b32 s30, s16, 3
	v_lshl_add_u64 v[132:133], v[132:133], 0, s[30:31]
	global_store_dwordx2 v[132:133], v[2:3], off sc1

.LBB0_368:
	s_andn2_saveexec_b64 s[28:29], s[28:29]
	s_cbranch_execz .LBB0_386
	s_mov_b64 s[28:29], exec
	s_waitcnt lgkmcnt(0)
	s_waitcnt vmcnt(0)
	v_mbcnt_lo_u32_b32 v0, s28, 0
	v_mbcnt_hi_u32_b32 v0, s29, v0
	v_cmp_eq_u32_e32 vcc, 0, v0
	s_and_saveexec_b64 s[38:39], vcc
	s_cbranch_execz .LBB0_371
	s_bcnt1_i32_b64 s9, s[28:29]
	v_readlane_b32 s28, v241, 13
	v_mov_b32_e32 v3, s9
	v_readlane_b32 s29, v241, 14
	s_nop 4
	global_atomic_add v3, v1, v3, s[28:29] sc0

.LBB0_662:
	s_andn2_saveexec_b64 s[28:29], s[28:29]
	s_cbranch_execz .LBB0_680
	s_mov_b64 s[28:29], exec
	s_waitcnt lgkmcnt(0)
	s_waitcnt vmcnt(0)
	v_mbcnt_lo_u32_b32 v0, s28, 0
	v_mbcnt_hi_u32_b32 v0, s29, v0
	v_cmp_eq_u32_e32 vcc, 0, v0
	s_and_saveexec_b64 s[40:41], vcc
	s_cbranch_execz .LBB0_665
	s_bcnt1_i32_b64 s9, s[28:29]
	v_readlane_b32 s28, v241, 13
	v_mov_b32_e32 v3, s9
	v_readlane_b32 s29, v241, 14
	s_nop 4
	global_atomic_add v3, v1, v3, s[28:29] sc0

.LBB0_700:
	v_mul_f32_e32 v150, v127, v127
	v_mul_f32_e32 v151, v129, v129
	v_fmac_f32_e32 v150, v126, v126
	v_fmac_f32_e32 v151, v128, v128
	v_add_f32_e32 v150, v150, v151
	v_mul_f32_e32 v151, v123, v123
	v_fmac_f32_e32 v151, v122, v122
	v_cvt_pk_bf16_f32 v126, v126, v127
	v_cvt_pk_bf16_f32 v127, v128, v129
	v_cvt_pk_bf16_f32 v128, v122, v123
	v_mul_f32_e32 v122, v119, v119
	v_mul_f32_e32 v123, v121, v121
	v_fmac_f32_e32 v122, v118, v118
	v_fmac_f32_e32 v123, v120, v120
	v_add_f32_e32 v122, v122, v123
	v_mul_f32_e32 v123, v115, v115
	v_fmac_f32_e32 v123, v114, v114
	v_add_f32_e32 v150, v150, v151
	v_mul_f32_e32 v151, v125, v125
	v_add_f32_e32 v122, v122, v123
	v_mul_f32_e32 v123, v117, v117
	v_fmac_f32_e32 v151, v124, v124
	v_fmac_f32_e32 v123, v116, v116
	v_add_f32_e32 v150, v151, v150
	v_cvt_pk_bf16_f32 v129, v124, v125
	v_add_f32_e32 v122, v123, v122
	v_and_b32_e32 v124, 64, v230
	v_add_f32_e32 v123, v150, v122
	v_xor_b32_e32 v122, 16, v230
	v_add_u32_e32 v150, 64, v124
	v_lshl_add_u32 v142, s30, 8, v144
	v_cmp_lt_i32_e32 vcc, v122, v150
	v_ashrrev_i32_e32 v143, 31, v142
	v_lshl_or_b32 v140, s75, 8, v146
	v_cndmask_b32_e32 v122, v230, v122, vcc
	v_lshlrev_b64 v[148:149], 11, v[142:143]
	v_lshlrev_b32_e32 v122, 2, v122
	v_ashrrev_i32_e32 v141, 31, v140
	ds_bpermute_b32 v151, v122, v123
	v_lshl_add_u64 v[124:125], s[28:29], 0, v[148:149]
	v_lshl_add_u64 v[148:149], v[140:141], 1, v[124:125]
	global_store_dwordx4 v[148:149], v[126:129], off sc1
	v_cvt_pk_bf16_f32 v124, v118, v119
	v_xor_b32_e32 v118, 32, v230
	v_cmp_lt_i32_e32 vcc, v118, v150
	s_waitcnt lgkmcnt(0)
	v_add_f32_e32 v119, v123, v151
	v_cvt_pk_bf16_f32 v125, v120, v121
	v_cvt_pk_bf16_f32 v126, v114, v115
	v_cvt_pk_bf16_f32 v127, v116, v117
	global_store_dwordx4 v[148:149], v[124:127], off offset:256 sc1
	v_cndmask_b32_e32 v118, v230, v118, vcc
	v_lshlrev_b32_e32 v118, 2, v118
	ds_bpermute_b32 v123, v118, v119
	s_and_saveexec_b64 s[64:65], s[38:39]
	s_cbranch_execz .LBB0_702
	s_lshl_b32 s66, s75, 2
	v_lshlrev_b64 v[114:115], 6, v[142:143]
	s_ashr_i32 s67, s66, 31
	v_lshl_add_u64 v[114:115], s[42:43], 0, v[114:115]
	v_lshl_add_u64 v[114:115], s[66:67], 2, v[114:115]
	s_lshl_b32 s30, s71, 2
	s_waitcnt lgkmcnt(0)
	v_add_f32_e32 v116, v119, v123
	v_lshl_add_u64 v[114:115], v[114:115], 0, s[30:31]
	global_store_dword v[114:115], v116, off sc1
.LBB0_702:
	s_or_b64 exec, exec, s[64:65]
	v_mul_f32_e32 v119, v111, v111
	v_mul_f32_e32 v120, v113, v113
	v_fmac_f32_e32 v119, v110, v110
	v_fmac_f32_e32 v120, v112, v112
	v_add_f32_e32 v119, v119, v120
	v_mul_f32_e32 v120, v107, v107
	v_fmac_f32_e32 v120, v106, v106
	v_cvt_pk_bf16_f32 v110, v110, v111
	v_cvt_pk_bf16_f32 v111, v112, v113
	v_cvt_pk_bf16_f32 v112, v106, v107
	v_mul_f32_e32 v106, v103, v103
	v_mul_f32_e32 v107, v105, v105
	v_fmac_f32_e32 v106, v102, v102
	v_fmac_f32_e32 v107, v104, v104
	v_add_f32_e32 v106, v106, v107
	v_mul_f32_e32 v107, v99, v99
	v_fmac_f32_e32 v107, v98, v98
	v_add_f32_e32 v119, v119, v120
	v_mul_f32_e32 v120, v109, v109
	v_add_f32_e32 v106, v106, v107
	v_mul_f32_e32 v107, v101, v101
	v_fmac_f32_e32 v120, v108, v108
	v_fmac_f32_e32 v107, v100, v100
	v_add_f32_e32 v119, v120, v119
	v_add_f32_e32 v106, v107, v106
	v_cvt_pk_bf16_f32 v113, v108, v109
	v_add_f32_e32 v108, v119, v106
	v_or_b32_e32 v114, 16, v142
	ds_bpermute_b32 v109, v122, v108
	v_ashrrev_i32_e32 v115, 31, v114
	v_lshlrev_b64 v[116:117], 11, v[114:115]
	v_lshl_add_u64 v[106:107], s[28:29], 0, v[116:117]
	v_lshl_add_u64 v[116:117], v[140:141], 1, v[106:107]
	global_store_dwordx4 v[116:117], v[110:113], off sc1
	v_cvt_pk_bf16_f32 v106, v102, v103
	s_waitcnt lgkmcnt(0)
	v_add_f32_e32 v102, v108, v109
	ds_bpermute_b32 v103, v118, v102
	v_cvt_pk_bf16_f32 v107, v104, v105
	v_cvt_pk_bf16_f32 v108, v98, v99
	v_cvt_pk_bf16_f32 v109, v100, v101
	global_store_dwordx4 v[116:117], v[106:109], off offset:256 sc1
	s_and_saveexec_b64 s[64:65], s[38:39]
	s_cbranch_execz .LBB0_704
	s_lshl_b32 s66, s75, 2
	v_lshlrev_b64 v[98:99], 6, v[114:115]
	s_ashr_i32 s67, s66, 31
	v_lshl_add_u64 v[98:99], s[42:43], 0, v[98:99]
	v_lshl_add_u64 v[98:99], s[66:67], 2, v[98:99]
	s_lshl_b32 s30, s71, 2
	s_waitcnt lgkmcnt(0)
	v_add_f32_e32 v100, v102, v103
	v_lshl_add_u64 v[98:99], v[98:99], 0, s[30:31]
	global_store_dword v[98:99], v100, off sc1
.LBB0_704:
	s_or_b64 exec, exec, s[64:65]
	v_mul_f32_e32 v102, v95, v95
	s_waitcnt lgkmcnt(0)
	v_mul_f32_e32 v103, v97, v97
	v_fmac_f32_e32 v102, v94, v94
	v_fmac_f32_e32 v103, v96, v96
	v_add_f32_e32 v102, v102, v103
	v_mul_f32_e32 v103, v91, v91
	v_fmac_f32_e32 v103, v90, v90
	v_cvt_pk_bf16_f32 v94, v94, v95
	v_cvt_pk_bf16_f32 v95, v96, v97
	v_cvt_pk_bf16_f32 v96, v90, v91
	v_mul_f32_e32 v90, v87, v87
	v_mul_f32_e32 v91, v89, v89
	v_fmac_f32_e32 v90, v86, v86
	v_fmac_f32_e32 v91, v88, v88
	v_add_f32_e32 v90, v90, v91
	v_mul_f32_e32 v91, v83, v83
	v_fmac_f32_e32 v91, v82, v82
	v_add_f32_e32 v102, v102, v103
	v_mul_f32_e32 v103, v93, v93
	v_add_f32_e32 v90, v90, v91
	v_mul_f32_e32 v91, v85, v85
	v_fmac_f32_e32 v103, v92, v92
	v_fmac_f32_e32 v91, v84, v84
	v_add_f32_e32 v102, v103, v102
	v_add_f32_e32 v90, v91, v90
	v_cvt_pk_bf16_f32 v97, v92, v93
	v_add_f32_e32 v92, v102, v90
	v_or_b32_e32 v98, 32, v142
	ds_bpermute_b32 v93, v122, v92
	v_ashrrev_i32_e32 v99, 31, v98
	v_lshlrev_b64 v[100:101], 11, v[98:99]
	v_lshl_add_u64 v[90:91], s[28:29], 0, v[100:101]
	v_lshl_add_u64 v[100:101], v[140:141], 1, v[90:91]
	global_store_dwordx4 v[100:101], v[94:97], off sc1
	v_cvt_pk_bf16_f32 v90, v86, v87
	s_waitcnt lgkmcnt(0)
	v_add_f32_e32 v86, v92, v93
	ds_bpermute_b32 v87, v118, v86
	v_cvt_pk_bf16_f32 v91, v88, v89
	v_cvt_pk_bf16_f32 v92, v82, v83
	v_cvt_pk_bf16_f32 v93, v84, v85
	global_store_dwordx4 v[100:101], v[90:93], off offset:256 sc1
	s_and_saveexec_b64 s[64:65], s[38:39]
	s_cbranch_execz .LBB0_706
	s_lshl_b32 s66, s75, 2
	v_lshlrev_b64 v[82:83], 6, v[98:99]
	s_ashr_i32 s67, s66, 31
	v_lshl_add_u64 v[82:83], s[42:43], 0, v[82:83]
	v_lshl_add_u64 v[82:83], s[66:67], 2, v[82:83]
	s_lshl_b32 s30, s71, 2
	s_waitcnt lgkmcnt(0)
	v_add_f32_e32 v84, v86, v87
	v_lshl_add_u64 v[82:83], v[82:83], 0, s[30:31]
	global_store_dword v[82:83], v84, off sc1
.LBB0_706:
	s_or_b64 exec, exec, s[64:65]
	v_mul_f32_e32 v86, v79, v79
	s_waitcnt lgkmcnt(0)
	v_mul_f32_e32 v87, v81, v81
	v_fmac_f32_e32 v86, v78, v78
	v_fmac_f32_e32 v87, v80, v80
	v_add_f32_e32 v86, v86, v87
	v_mul_f32_e32 v87, v75, v75
	v_fmac_f32_e32 v87, v74, v74
	v_cvt_pk_bf16_f32 v78, v78, v79
	v_cvt_pk_bf16_f32 v79, v80, v81
	v_cvt_pk_bf16_f32 v80, v74, v75
	v_mul_f32_e32 v74, v71, v71
	v_mul_f32_e32 v75, v73, v73
	v_fmac_f32_e32 v74, v70, v70
	v_fmac_f32_e32 v75, v72, v72
	v_add_f32_e32 v74, v74, v75
	v_mul_f32_e32 v75, v67, v67
	v_fmac_f32_e32 v75, v66, v66
	v_add_f32_e32 v86, v86, v87
	v_mul_f32_e32 v87, v77, v77
	v_add_f32_e32 v74, v74, v75
	v_mul_f32_e32 v75, v69, v69
	v_fmac_f32_e32 v87, v76, v76
	v_fmac_f32_e32 v75, v68, v68
	v_add_f32_e32 v86, v87, v86
	v_add_f32_e32 v74, v75, v74
	v_cvt_pk_bf16_f32 v81, v76, v77
	v_add_f32_e32 v76, v86, v74
	v_or_b32_e32 v82, 48, v142
	ds_bpermute_b32 v77, v122, v76
	v_ashrrev_i32_e32 v83, 31, v82
	v_lshlrev_b64 v[84:85], 11, v[82:83]
	v_lshl_add_u64 v[74:75], s[28:29], 0, v[84:85]
	v_lshl_add_u64 v[84:85], v[140:141], 1, v[74:75]
	global_store_dwordx4 v[84:85], v[78:81], off sc1
	v_cvt_pk_bf16_f32 v74, v70, v71
	s_waitcnt lgkmcnt(0)
	v_add_f32_e32 v70, v76, v77
	ds_bpermute_b32 v71, v118, v70
	v_cvt_pk_bf16_f32 v75, v72, v73
	v_cvt_pk_bf16_f32 v76, v66, v67
	v_cvt_pk_bf16_f32 v77, v68, v69
	global_store_dwordx4 v[84:85], v[74:77], off offset:256 sc1
	s_and_saveexec_b64 s[64:65], s[38:39]
	s_cbranch_execz .LBB0_708
	s_lshl_b32 s66, s75, 2
	v_lshlrev_b64 v[66:67], 6, v[82:83]
	s_ashr_i32 s67, s66, 31
	v_lshl_add_u64 v[66:67], s[42:43], 0, v[66:67]
	v_lshl_add_u64 v[66:67], s[66:67], 2, v[66:67]
	s_lshl_b32 s30, s71, 2
	s_waitcnt lgkmcnt(0)
	v_add_f32_e32 v68, v70, v71
	v_lshl_add_u64 v[66:67], v[66:67], 0, s[30:31]
	global_store_dword v[66:67], v68, off sc1
.LBB0_708:
	s_or_b64 exec, exec, s[64:65]
	v_mul_f32_e32 v70, v63, v63
	s_waitcnt lgkmcnt(0)
	v_mul_f32_e32 v71, v65, v65
	v_fmac_f32_e32 v70, v62, v62
	v_fmac_f32_e32 v71, v64, v64
	v_add_f32_e32 v70, v70, v71
	v_mul_f32_e32 v71, v59, v59
	v_fmac_f32_e32 v71, v58, v58
	v_cvt_pk_bf16_f32 v62, v62, v63
	v_cvt_pk_bf16_f32 v63, v64, v65
	v_cvt_pk_bf16_f32 v64, v58, v59
	v_mul_f32_e32 v58, v55, v55
	v_mul_f32_e32 v59, v57, v57
	v_fmac_f32_e32 v58, v54, v54
	v_fmac_f32_e32 v59, v56, v56
	v_add_f32_e32 v58, v58, v59
	v_mul_f32_e32 v59, v51, v51
	v_fmac_f32_e32 v59, v50, v50
	v_add_f32_e32 v70, v70, v71
	v_mul_f32_e32 v71, v61, v61
	v_add_f32_e32 v58, v58, v59
	v_mul_f32_e32 v59, v53, v53
	v_fmac_f32_e32 v71, v60, v60
	v_fmac_f32_e32 v59, v52, v52
	v_add_f32_e32 v70, v71, v70
	v_add_f32_e32 v58, v59, v58
	v_cvt_pk_bf16_f32 v65, v60, v61
	v_add_f32_e32 v60, v70, v58
	v_add_u32_e32 v66, 0x80, v142
	ds_bpermute_b32 v61, v122, v60
	v_ashrrev_i32_e32 v67, 31, v66
	v_lshlrev_b64 v[68:69], 11, v[66:67]
	v_lshl_add_u64 v[58:59], s[28:29], 0, v[68:69]
	v_lshl_add_u64 v[68:69], v[140:141], 1, v[58:59]
	global_store_dwordx4 v[68:69], v[62:65], off sc1
	v_cvt_pk_bf16_f32 v58, v54, v55
	s_waitcnt lgkmcnt(0)
	v_add_f32_e32 v54, v60, v61
	ds_bpermute_b32 v55, v118, v54
	v_cvt_pk_bf16_f32 v59, v56, v57
	v_cvt_pk_bf16_f32 v60, v50, v51
	v_cvt_pk_bf16_f32 v61, v52, v53
	global_store_dwordx4 v[68:69], v[58:61], off offset:256 sc1
	s_and_saveexec_b64 s[64:65], s[38:39]
	s_cbranch_execz .LBB0_710
	s_lshl_b32 s66, s75, 2
	v_lshlrev_b64 v[50:51], 6, v[66:67]
	s_ashr_i32 s67, s66, 31
	v_lshl_add_u64 v[50:51], s[42:43], 0, v[50:51]
	v_lshl_add_u64 v[50:51], s[66:67], 2, v[50:51]
	s_lshl_b32 s30, s71, 2
	s_waitcnt lgkmcnt(0)
	v_add_f32_e32 v52, v54, v55
	v_lshl_add_u64 v[50:51], v[50:51], 0, s[30:31]
	global_store_dword v[50:51], v52, off sc1
.LBB0_710:
	s_or_b64 exec, exec, s[64:65]
	v_mul_f32_e32 v54, v47, v47
	s_waitcnt lgkmcnt(0)
	v_mul_f32_e32 v55, v49, v49
	v_fmac_f32_e32 v54, v46, v46
	v_fmac_f32_e32 v55, v48, v48
	v_add_f32_e32 v54, v54, v55
	v_mul_f32_e32 v55, v43, v43
	v_fmac_f32_e32 v55, v42, v42
	v_cvt_pk_bf16_f32 v46, v46, v47
	v_cvt_pk_bf16_f32 v47, v48, v49
	v_cvt_pk_bf16_f32 v48, v42, v43
	v_mul_f32_e32 v42, v39, v39
	v_mul_f32_e32 v43, v41, v41
	v_fmac_f32_e32 v42, v38, v38
	v_fmac_f32_e32 v43, v40, v40
	v_add_f32_e32 v42, v42, v43
	v_mul_f32_e32 v43, v35, v35
	v_fmac_f32_e32 v43, v34, v34
	v_add_f32_e32 v54, v54, v55
	v_mul_f32_e32 v55, v45, v45
	v_add_f32_e32 v42, v42, v43
	v_mul_f32_e32 v43, v37, v37
	v_fmac_f32_e32 v55, v44, v44
	v_fmac_f32_e32 v43, v36, v36
	v_add_f32_e32 v54, v55, v54
	v_add_f32_e32 v42, v43, v42
	v_cvt_pk_bf16_f32 v49, v44, v45
	v_add_f32_e32 v44, v54, v42
	v_add_u32_e32 v50, 0x90, v142
	ds_bpermute_b32 v45, v122, v44
	v_ashrrev_i32_e32 v51, 31, v50
	v_lshlrev_b64 v[52:53], 11, v[50:51]
	v_lshl_add_u64 v[42:43], s[28:29], 0, v[52:53]
	v_lshl_add_u64 v[52:53], v[140:141], 1, v[42:43]
	global_store_dwordx4 v[52:53], v[46:49], off sc1
	v_cvt_pk_bf16_f32 v42, v38, v39
	s_waitcnt lgkmcnt(0)
	v_add_f32_e32 v38, v44, v45
	ds_bpermute_b32 v39, v118, v38
	v_cvt_pk_bf16_f32 v43, v40, v41
	v_cvt_pk_bf16_f32 v44, v34, v35
	v_cvt_pk_bf16_f32 v45, v36, v37
	global_store_dwordx4 v[52:53], v[42:45], off offset:256 sc1
	s_and_saveexec_b64 s[64:65], s[38:39]
	s_cbranch_execz .LBB0_712
	s_lshl_b32 s66, s75, 2
	v_lshlrev_b64 v[34:35], 6, v[50:51]
	s_ashr_i32 s67, s66, 31
	v_lshl_add_u64 v[34:35], s[42:43], 0, v[34:35]
	v_lshl_add_u64 v[34:35], s[66:67], 2, v[34:35]
	s_lshl_b32 s30, s71, 2
	s_waitcnt lgkmcnt(0)
	v_add_f32_e32 v36, v38, v39
	v_lshl_add_u64 v[34:35], v[34:35], 0, s[30:31]
	global_store_dword v[34:35], v36, off sc1
.LBB0_712:
	s_or_b64 exec, exec, s[64:65]
	v_mul_f32_e32 v38, v31, v31
	s_waitcnt lgkmcnt(0)
	v_mul_f32_e32 v39, v33, v33
	v_fmac_f32_e32 v38, v30, v30
	v_fmac_f32_e32 v39, v32, v32
	v_add_f32_e32 v38, v38, v39
	v_mul_f32_e32 v39, v27, v27
	v_fmac_f32_e32 v39, v26, v26
	v_cvt_pk_bf16_f32 v30, v30, v31
	v_cvt_pk_bf16_f32 v31, v32, v33
	v_cvt_pk_bf16_f32 v32, v26, v27
	v_mul_f32_e32 v26, v23, v23
	v_mul_f32_e32 v27, v25, v25
	v_fmac_f32_e32 v26, v22, v22
	v_fmac_f32_e32 v27, v24, v24
	v_add_f32_e32 v26, v26, v27
	v_mul_f32_e32 v27, v19, v19
	v_fmac_f32_e32 v27, v18, v18
	v_add_f32_e32 v38, v38, v39
	v_mul_f32_e32 v39, v29, v29
	v_add_f32_e32 v26, v26, v27
	v_mul_f32_e32 v27, v21, v21
	v_fmac_f32_e32 v39, v28, v28
	v_fmac_f32_e32 v27, v20, v20
	v_add_f32_e32 v38, v39, v38
	v_add_f32_e32 v26, v27, v26
	v_cvt_pk_bf16_f32 v33, v28, v29
	v_add_f32_e32 v28, v38, v26
	v_add_u32_e32 v34, 0xa0, v142
	ds_bpermute_b32 v29, v122, v28
	v_ashrrev_i32_e32 v35, 31, v34
	v_lshlrev_b64 v[36:37], 11, v[34:35]
	v_lshl_add_u64 v[26:27], s[28:29], 0, v[36:37]
	v_lshl_add_u64 v[36:37], v[140:141], 1, v[26:27]
	global_store_dwordx4 v[36:37], v[30:33], off sc1
	v_cvt_pk_bf16_f32 v26, v22, v23
	s_waitcnt lgkmcnt(0)
	v_add_f32_e32 v22, v28, v29
	ds_bpermute_b32 v23, v118, v22
	v_cvt_pk_bf16_f32 v27, v24, v25
	v_cvt_pk_bf16_f32 v28, v18, v19
	v_cvt_pk_bf16_f32 v29, v20, v21
	global_store_dwordx4 v[36:37], v[26:29], off offset:256 sc1
	s_and_saveexec_b64 s[64:65], s[38:39]
	s_cbranch_execz .LBB0_714
	s_lshl_b32 s66, s75, 2
	v_lshlrev_b64 v[18:19], 6, v[34:35]
	s_ashr_i32 s67, s66, 31
	v_lshl_add_u64 v[18:19], s[42:43], 0, v[18:19]
	v_lshl_add_u64 v[18:19], s[66:67], 2, v[18:19]
	s_lshl_b32 s30, s71, 2
	s_waitcnt lgkmcnt(0)
	v_add_f32_e32 v20, v22, v23
	v_lshl_add_u64 v[18:19], v[18:19], 0, s[30:31]
	global_store_dword v[18:19], v20, off sc1
.LBB0_714:
	s_or_b64 exec, exec, s[64:65]
	v_mul_f32_e32 v22, v15, v15
	s_waitcnt lgkmcnt(0)
	v_mul_f32_e32 v23, v17, v17
	v_fmac_f32_e32 v22, v14, v14
	v_fmac_f32_e32 v23, v16, v16
	v_add_f32_e32 v22, v22, v23
	v_mul_f32_e32 v23, v11, v11
	v_fmac_f32_e32 v23, v10, v10
	v_cvt_pk_bf16_f32 v14, v14, v15
	v_cvt_pk_bf16_f32 v15, v16, v17
	v_cvt_pk_bf16_f32 v16, v10, v11
	v_mul_f32_e32 v10, v7, v7
	v_mul_f32_e32 v11, v9, v9
	v_fmac_f32_e32 v10, v6, v6
	v_fmac_f32_e32 v11, v8, v8
	v_add_f32_e32 v10, v10, v11
	v_mul_f32_e32 v11, v3, v3
	v_fmac_f32_e32 v11, v2, v2
	v_add_f32_e32 v22, v22, v23
	v_mul_f32_e32 v23, v13, v13
	v_add_f32_e32 v10, v10, v11
	v_mul_f32_e32 v11, v5, v5
	v_fmac_f32_e32 v23, v12, v12
	v_fmac_f32_e32 v11, v4, v4
	v_add_f32_e32 v22, v23, v22
	v_add_f32_e32 v10, v11, v10
	v_cvt_pk_bf16_f32 v17, v12, v13
	v_add_f32_e32 v12, v22, v10
	v_add_u32_e32 v18, 0xb0, v142
	ds_bpermute_b32 v13, v122, v12
	v_ashrrev_i32_e32 v19, 31, v18
	v_lshlrev_b64 v[20:21], 11, v[18:19]
	v_lshl_add_u64 v[10:11], s[28:29], 0, v[20:21]
	v_lshl_add_u64 v[20:21], v[140:141], 1, v[10:11]
	global_store_dwordx4 v[20:21], v[14:17], off sc1
	v_cvt_pk_bf16_f32 v10, v6, v7
	s_waitcnt lgkmcnt(0)
	v_add_f32_e32 v6, v12, v13
	ds_bpermute_b32 v7, v118, v6
	v_cvt_pk_bf16_f32 v11, v8, v9
	v_cvt_pk_bf16_f32 v12, v2, v3
	v_cvt_pk_bf16_f32 v13, v4, v5
	global_store_dwordx4 v[20:21], v[10:13], off offset:256 sc1
	s_and_saveexec_b64 s[64:65], s[38:39]
	s_cbranch_execz .LBB0_716
	s_lshl_b32 s66, s75, 2
	v_lshlrev_b64 v[2:3], 6, v[18:19]
	s_ashr_i32 s67, s66, 31
	v_lshl_add_u64 v[2:3], s[42:43], 0, v[2:3]
	v_lshl_add_u64 v[2:3], s[66:67], 2, v[2:3]
	s_lshl_b32 s30, s71, 2
	s_waitcnt lgkmcnt(0)
	v_add_f32_e32 v4, v6, v7
	v_lshl_add_u64 v[2:3], v[2:3], 0, s[30:31]
	global_store_dword v[2:3], v4, off sc1

.LBB0_787:
	s_add_i32 s16, s56, s8
	s_cmpk_lt_i32 s16, 0x4000
	s_cselect_b64 s[44:45], -1, 0
	s_and_b64 s[38:39], s[44:45], exec
	s_cselect_b32 s42, s16, s8
	s_add_u32 s40, s26, s28
	s_addc_u32 s41, s27, s29
	s_add_u32 s46, s40, 0x2700000
	s_addc_u32 s47, s41, 0
	s_ashr_i32 s43, s42, 31
	s_lshl_b64 s[38:39], s[42:43], 6
	s_add_u32 s38, s9, s38
	s_addc_u32 s39, s13, s39
	global_load_dwordx4 v[34:37], v1, s[46:47] offset:48
	global_load_dwordx4 v[38:41], v1, s[46:47] offset:32
	global_load_dwordx4 v[42:45], v1, s[46:47] offset:16
	global_load_dwordx4 v[46:49], v229, s[40:41]
	global_load_dwordx4 v[50:53], v1, s[38:39] offset:48
	global_load_dwordx4 v[54:57], v1, s[38:39] offset:32
	global_load_dwordx4 v[70:73], v1, s[38:39] offset:16
	global_load_dwordx4 v[74:77], v1, s[38:39]
	s_lshl_b64 s[46:47], s[42:43], 11
	s_lshl_b64 s[50:51], s[42:43], 12
	s_cmpk_gt_i32 s16, 0x3fff
	s_brev_b32 s16, 16
	v_lshl_add_u64 v[90:91], v[58:59], 0, s[46:47]
	v_lshl_add_u64 v[84:85], v[60:61], 0, s[50:51]
	s_waitcnt vmcnt(6)
	v_add_f32_e32 v38, v38, v39
	v_add_f32_e32 v40, v40, v41
	s_waitcnt vmcnt(4)
	v_mov_b32_e32 v78, v47
	v_mov_b32_e32 v79, v48
	v_mov_b32_e32 v47, v49
	v_mov_b32_e32 v48, v43
	v_mov_b32_e32 v49, v44
	v_mov_b32_e32 v43, v45
	v_pk_add_f32 v[46:47], v[78:79], v[46:47]
	v_pk_add_f32 v[42:43], v[48:49], v[42:43]
	v_pk_add_f32 v[46:47], v[46:47], v[46:47] op_sel:[0,1] op_sel_hi:[1,0]
	v_pk_add_f32 v[42:43], v[42:43], v[42:43] op_sel:[0,1] op_sel_hi:[1,0]
	v_mov_b32_e32 v47, v34
	v_mov_b32_e32 v43, v35
	v_mov_b32_e32 v39, v36
	v_mov_b32_e32 v41, v37
	v_pk_add_f32 v[34:35], v[46:47], v[42:43]
	v_pk_add_f32 v[36:37], v[38:39], v[40:41]
	s_waitcnt vmcnt(2)
	v_add_f32_e32 v38, v54, v55
	v_pk_add_f32 v[34:35], v[34:35], v[36:37]
	s_waitcnt vmcnt(1)
	v_mov_b32_e32 v36, v71
	v_add_f32_e32 v0, v34, v35
	s_waitcnt vmcnt(0)
	v_mov_b32_e32 v34, v75
	v_mov_b32_e32 v35, v76
	v_mov_b32_e32 v75, v77
	v_mov_b32_e32 v37, v72
	v_mov_b32_e32 v71, v73
	v_pk_add_f32 v[34:35], v[34:35], v[74:75]
	v_pk_add_f32 v[36:37], v[36:37], v[70:71]
	v_pk_add_f32 v[34:35], v[34:35], v[34:35] op_sel:[0,1] op_sel_hi:[1,0]
	v_pk_add_f32 v[36:37], v[36:37], v[36:37] op_sel:[0,1] op_sel_hi:[1,0]
	v_add_f32_e32 v40, v56, v57
	v_mov_b32_e32 v35, v50
	v_mov_b32_e32 v37, v51
	v_mov_b32_e32 v39, v52
	v_mov_b32_e32 v41, v53
	v_pk_add_f32 v[34:35], v[34:35], v[36:37]
	v_pk_add_f32 v[36:37], v[38:39], v[40:41]
	v_fmamk_f32 v0, v0, 0x3a800000, v227
	v_pk_add_f32 v[34:35], v[34:35], v[36:37]
	v_cmp_gt_f32_e32 vcc, s7, v0
	v_add_f32_e32 v34, v34, v35
	v_mul_f32_e32 v35, 0x4f800000, v0
	v_cndmask_b32_e32 v0, v0, v35, vcc
	v_sqrt_f32_e32 v35, v0
	v_fmamk_f32 v34, v34, 0x3a800000, v227
	v_cmp_gt_f32_e64 s[38:39], s7, v34
	v_mul_f32_e32 v38, 0x4f800000, v34
	v_add_u32_e32 v37, -1, v35
	v_fma_f32 v41, -v37, v35, v0
	v_add_u32_e32 v36, 1, v35
	v_cmp_ge_f32_e64 s[40:41], 0, v41
	v_cndmask_b32_e64 v34, v34, v38, s[38:39]
	v_sqrt_f32_e32 v38, v34
	v_cndmask_b32_e64 v37, v35, v37, s[40:41]
	v_fma_f32 v35, -v36, v35, v0
	v_cmp_lt_f32_e64 s[40:41], 0, v35
	v_add_u32_e32 v40, -1, v38
	v_add_u32_e32 v39, 1, v38
	v_cndmask_b32_e64 v35, v37, v36, s[40:41]
	v_mul_f32_e32 v36, 0x37800000, v35
	v_cndmask_b32_e32 v35, v35, v36, vcc
	v_cmp_class_f32_e32 vcc, v0, v228
	v_lshl_add_u64 v[70:71], s[26:27], 0, v[68:69]
	s_nop 0
	v_cndmask_b32_e32 v0, v35, v0, vcc
	v_div_scale_f32 v35, s[40:41], v0, v0, 1.0
	v_rcp_f32_e32 v36, v35
	s_nop 0
	v_fma_f32 v37, -v35, v36, 1.0
	v_fmac_f32_e32 v36, v37, v36
	v_div_scale_f32 v37, vcc, 1.0, v0, 1.0
	v_mul_f32_e32 v41, v37, v36
	v_fma_f32 v42, -v35, v41, v37
	v_fmac_f32_e32 v41, v42, v36
	v_fma_f32 v35, -v35, v41, v37
	v_div_fmas_f32 v35, v35, v36, v41
	v_div_fixup_f32 v80, v35, v0, 1.0
	v_fma_f32 v0, -v40, v38, v34
	v_cmp_ge_f32_e32 vcc, 0, v0
	v_fma_f32 v35, -v39, v38, v34
	s_nop 0
	v_cndmask_b32_e32 v0, v38, v40, vcc
	v_cmp_lt_f32_e32 vcc, 0, v35
	s_nop 1
	v_cndmask_b32_e32 v0, v0, v39, vcc
	v_mul_f32_e32 v35, 0x37800000, v0
	v_cndmask_b32_e64 v0, v0, v35, s[38:39]
	v_cmp_class_f32_e32 vcc, v34, v228
	s_nop 1
	v_cndmask_b32_e32 v0, v0, v34, vcc
	v_div_scale_f32 v34, s[38:39], v0, v0, 1.0
	v_rcp_f32_e32 v35, v34
	s_nop 0
	v_fma_f32 v36, -v34, v35, 1.0
	v_fmac_f32_e32 v35, v36, v35
	v_div_scale_f32 v36, vcc, 1.0, v0, 1.0
	v_mul_f32_e32 v37, v36, v35
	v_fma_f32 v38, -v34, v37, v36
	v_fmac_f32_e32 v37, v38, v35
	v_fma_f32 v34, -v34, v37, v36
	v_div_fmas_f32 v34, v34, v35, v37
	v_add_co_u32_e32 v96, vcc, s16, v70
	v_div_fixup_f32 v82, v34, v0, 1.0
	s_nop 0
	v_addc_co_u32_e32 v97, vcc, 0, v71, vcc
	global_load_dwordx4 v[34:37], v[66:67], off
	global_load_dwordx4 v[38:41], v[84:85], off
	global_load_dwordx2 v[42:43], v[96:97], off
	global_load_dwordx2 v[44:45], v[90:91], off
	v_add_co_u32_e32 v102, vcc, 0xe000000, v70
	s_waitcnt vmcnt(1)
	v_lshlrev_b32_e32 v46, 16, v42
	v_and_b32_e32 v47, 0xffff0000, v42
	v_lshlrev_b32_e32 v42, 16, v43
	v_and_b32_e32 v43, 0xffff0000, v43
	s_waitcnt vmcnt(0)
	v_lshlrev_b32_e32 v48, 16, v44
	v_and_b32_e32 v49, 0xffff0000, v44
	v_lshlrev_b32_e32 v44, 16, v45
	v_and_b32_e32 v45, 0xffff0000, v45
	v_pk_mul_f32 v[46:47], v[80:81], v[46:47] op_sel_hi:[0,1]
	v_pk_mul_f32 v[42:43], v[80:81], v[42:43] op_sel_hi:[0,1]
	v_pk_fma_f32 v[76:77], v[4:5], v[42:43], v[36:37]
	v_pk_fma_f32 v[78:79], v[2:3], v[46:47], v[34:35]
	v_pk_mul_f32 v[34:35], v[82:83], v[48:49] op_sel_hi:[0,1]
	v_pk_mul_f32 v[36:37], v[82:83], v[44:45] op_sel_hi:[0,1]
	v_pk_fma_f32 v[72:73], v[4:5], v[36:37], v[40:41]
	v_pk_fma_f32 v[74:75], v[2:3], v[34:35], v[38:39]
	global_load_dwordx4 v[54:57], v[66:67], off offset:1024
	global_load_dwordx4 v[50:53], v[84:85], off offset:1024
	global_load_dwordx2 v[94:95], v[96:97], off offset:512
	global_load_dwordx2 v[92:93], v[90:91], off offset:512
	global_load_dwordx4 v[46:49], v[66:67], off offset:2048
	global_load_dwordx4 v[42:45], v[84:85], off offset:2048
	global_load_dwordx2 v[88:89], v[96:97], off offset:1024
	global_load_dwordx2 v[86:87], v[90:91], off offset:1024
	global_load_dwordx4 v[38:41], v[66:67], off offset:3072
	global_load_dwordx4 v[34:37], v[84:85], off offset:3072
	s_nop 0
	global_load_dwordx2 v[84:85], v[96:97], off offset:1536
	s_nop 0
	global_load_dwordx2 v[90:91], v[90:91], off offset:1536
	v_lshl_add_u64 v[96:97], v[62:63], 0, s[46:47]
	v_addc_co_u32_e32 v103, vcc, 0, v71, vcc
	v_cvt_pk_bf16_f32 v100, v78, v79
	v_cvt_pk_bf16_f32 v101, v76, v77
	v_cvt_pk_bf16_f32 v98, v74, v75
	v_cvt_pk_bf16_f32 v99, v72, v73
	global_store_dwordx2 v[102:103], v[100:101], off sc1
	s_cbranch_scc1 .LBB0_789
	global_store_dwordx2 v[96:97], v[98:99], off sc1
.LBB0_789:
	s_waitcnt vmcnt(10)
	v_lshlrev_b32_e32 v98, 16, v94
	v_and_b32_e32 v99, 0xffff0000, v94
	v_lshlrev_b32_e32 v94, 16, v95
	v_and_b32_e32 v95, 0xffff0000, v95
	s_waitcnt vmcnt(9)
	v_lshlrev_b32_e32 v100, 16, v92
	v_and_b32_e32 v101, 0xffff0000, v92
	v_lshlrev_b32_e32 v102, 16, v93
	v_and_b32_e32 v103, 0xffff0000, v93
	v_mov_b32_e32 v92, v80
	v_mov_b32_e32 v93, v80
	v_mov_b32_e32 v81, v80
	v_pk_mul_f32 v[94:95], v[92:93], v[94:95]
	v_mov_b32_e32 v83, v82
	v_pk_mul_f32 v[98:99], v[80:81], v[98:99]
	v_pk_fma_f32 v[56:57], v[8:9], v[94:95], v[56:57]
	v_mov_b32_e32 v94, v82
	v_mov_b32_e32 v95, v82
	v_pk_fma_f32 v[54:55], v[6:7], v[98:99], v[54:55]
	v_pk_mul_f32 v[98:99], v[82:83], v[100:101]
	v_pk_mul_f32 v[100:101], v[94:95], v[102:103]
	v_add_co_u32_e32 v102, vcc, 0xe000000, v70
	v_cndmask_b32_e64 v0, 0, 1, s[44:45]
	s_nop 0
	v_addc_co_u32_e32 v103, vcc, 0, v71, vcc
	v_pk_fma_f32 v[52:53], v[8:9], v[100:101], v[52:53]
	v_pk_fma_f32 v[50:51], v[6:7], v[98:99], v[50:51]
	v_cmp_ne_u32_e64 s[38:39], 1, v0
	s_andn2_b64 vcc, exec, s[44:45]
	v_cvt_pk_bf16_f32 v100, v54, v55
	v_cvt_pk_bf16_f32 v101, v56, v57
	v_cvt_pk_bf16_f32 v98, v50, v51
	v_cvt_pk_bf16_f32 v99, v52, v53
	global_store_dwordx2 v[102:103], v[100:101], off offset:512 sc1
	s_cbranch_vccnz .LBB0_791
	global_store_dwordx2 v[96:97], v[98:99], off offset:512 sc1
.LBB0_791:
	s_waitcnt vmcnt(7)
	v_lshlrev_b32_e32 v98, 16, v88
	v_and_b32_e32 v99, 0xffff0000, v88
	v_lshlrev_b32_e32 v88, 16, v89
	v_and_b32_e32 v89, 0xffff0000, v89
	s_waitcnt vmcnt(6)
	v_lshlrev_b32_e32 v100, 16, v86
	v_and_b32_e32 v101, 0xffff0000, v86
	v_lshlrev_b32_e32 v86, 16, v87
	v_and_b32_e32 v87, 0xffff0000, v87
	v_pk_mul_f32 v[88:89], v[92:93], v[88:89]
	v_add_co_u32_e32 v92, vcc, 0xe000000, v70
	v_pk_mul_f32 v[98:99], v[80:81], v[98:99]
	v_pk_fma_f32 v[48:49], v[12:13], v[88:89], v[48:49]
	v_pk_mul_f32 v[88:89], v[82:83], v[100:101]
	v_pk_mul_f32 v[86:87], v[94:95], v[86:87]
	v_addc_co_u32_e32 v93, vcc, 0, v71, vcc
	v_pk_fma_f32 v[46:47], v[10:11], v[98:99], v[46:47]
	v_pk_fma_f32 v[44:45], v[12:13], v[86:87], v[44:45]
	v_pk_fma_f32 v[42:43], v[10:11], v[88:89], v[42:43]
	s_and_b64 vcc, exec, s[38:39]
	v_cvt_pk_bf16_f32 v88, v46, v47
	v_cvt_pk_bf16_f32 v89, v48, v49
	v_cvt_pk_bf16_f32 v86, v42, v43
	v_cvt_pk_bf16_f32 v87, v44, v45
	global_store_dwordx2 v[92:93], v[88:89], off offset:1024 sc1
	s_cbranch_vccnz .LBB0_793
	global_store_dwordx2 v[96:97], v[86:87], off offset:1024 sc1
.LBB0_793:
	s_waitcnt vmcnt(4)
	v_lshlrev_b32_e32 v86, 16, v84
	v_and_b32_e32 v87, 0xffff0000, v84
	v_lshlrev_b32_e32 v84, 16, v85
	v_and_b32_e32 v85, 0xffff0000, v85
	v_pk_mul_f32 v[86:87], v[80:81], v[86:87]
	v_mov_b32_e32 v81, v80
	s_waitcnt vmcnt(3)
	v_lshlrev_b32_e32 v88, 16, v90
	v_and_b32_e32 v89, 0xffff0000, v90
	v_pk_mul_f32 v[80:81], v[80:81], v[84:85]
	v_lshlrev_b32_e32 v90, 16, v91
	v_and_b32_e32 v91, 0xffff0000, v91
	v_pk_fma_f32 v[40:41], v[16:17], v[80:81], v[40:41]
	v_pk_mul_f32 v[80:81], v[82:83], v[88:89]
	v_mov_b32_e32 v83, v82
	v_add_co_u32_e32 v84, vcc, 0xe000000, v70
	v_pk_mul_f32 v[82:83], v[82:83], v[90:91]
	s_nop 0
	v_addc_co_u32_e32 v85, vcc, 0, v71, vcc
	v_pk_fma_f32 v[38:39], v[14:15], v[86:87], v[38:39]
	v_pk_fma_f32 v[36:37], v[16:17], v[82:83], v[36:37]
	v_pk_fma_f32 v[34:35], v[14:15], v[80:81], v[34:35]
	s_and_b64 vcc, exec, s[38:39]
	v_cvt_pk_bf16_f32 v82, v38, v39
	v_cvt_pk_bf16_f32 v83, v40, v41
	v_cvt_pk_bf16_f32 v80, v34, v35
	v_cvt_pk_bf16_f32 v81, v36, v37
	global_store_dwordx2 v[84:85], v[82:83], off offset:1536 sc1
	s_cbranch_vccnz .LBB0_795
	global_store_dwordx2 v[96:97], v[80:81], off offset:1536 sc1
.LBB0_795:
	v_mul_f32_e32 v82, v55, v55
	v_mul_f32_e32 v83, v56, v56
	v_fmac_f32_e32 v82, v54, v54
	v_fmac_f32_e32 v83, v57, v57
	v_add_f32_e32 v82, v82, v83
	v_mul_f32_e32 v83, v51, v51
	v_mul_f32_e32 v84, v53, v53
	v_mul_f32_e32 v0, v79, v79
	v_mul_f32_e32 v80, v76, v76
	v_fmac_f32_e32 v83, v50, v50
	v_fmac_f32_e32 v84, v52, v52
	v_fmac_f32_e32 v0, v78, v78
	v_fmac_f32_e32 v80, v77, v77
	v_add_f32_e32 v83, v83, v84
	v_mul_f32_e32 v84, v47, v47
	v_mul_f32_e32 v85, v48, v48
	v_add_f32_e32 v0, v0, v80
	v_mul_f32_e32 v80, v75, v75
	v_mul_f32_e32 v81, v73, v73
	v_fmac_f32_e32 v84, v46, v46
	v_fmac_f32_e32 v85, v49, v49
	v_fmac_f32_e32 v81, v72, v72
	v_add_f32_e32 v84, v84, v85
	v_mul_f32_e32 v85, v43, v43
	v_mul_f32_e32 v86, v45, v45
	v_fmac_f32_e32 v80, v74, v74
	v_fmac_f32_e32 v85, v42, v42
	v_fmac_f32_e32 v86, v44, v44
	v_add_f32_e32 v80, v80, v81
	v_and_b32_e32 v81, 64, v230
	v_add_f32_e32 v85, v85, v86
	v_mul_f32_e32 v86, v39, v39
	v_mul_f32_e32 v87, v40, v40
	v_add_f32_e32 v0, v0, v82
	v_add_u32_e32 v81, 64, v81
	v_xor_b32_e32 v82, 1, v230
	v_fmac_f32_e32 v86, v38, v38
	v_fmac_f32_e32 v87, v41, v41
	v_cmp_lt_i32_e32 vcc, v82, v81
	v_add_f32_e32 v86, v86, v87
	v_add_f32_e32 v0, v0, v84
	v_cndmask_b32_e32 v82, v230, v82, vcc
	v_add_f32_e32 v0, v0, v86
	v_lshlrev_b32_e32 v82, 2, v82
	v_add_f32_e32 v80, v80, v83
	ds_bpermute_b32 v83, v82, v0
	v_add_f32_e32 v80, v80, v85
	v_mul_f32_e32 v87, v35, v35
	v_mul_f32_e32 v88, v37, v37
	v_fmac_f32_e32 v87, v34, v34
	s_waitcnt lgkmcnt(0)
	v_add_f32_e32 v0, v0, v83
	v_xor_b32_e32 v83, 2, v230
	v_cmp_lt_i32_e32 vcc, v83, v81
	v_fmac_f32_e32 v88, v36, v36
	v_add_f32_e32 v87, v87, v88
	v_cndmask_b32_e32 v83, v230, v83, vcc
	v_lshlrev_b32_e32 v83, 2, v83
	ds_bpermute_b32 v84, v83, v0
	v_add_f32_e32 v80, v80, v87
	ds_bpermute_b32 v82, v82, v80
	s_lshl_b64 s[42:43], s[42:43], 10
	s_waitcnt lgkmcnt(1)
	v_add_f32_e32 v0, v0, v84
	v_xor_b32_e32 v84, 4, v230
	v_cmp_lt_i32_e32 vcc, v84, v81
	s_waitcnt lgkmcnt(0)
	v_add_f32_e32 v80, v80, v82
	ds_bpermute_b32 v82, v83, v80
	v_cndmask_b32_e32 v84, v230, v84, vcc
	v_lshlrev_b32_e32 v84, 2, v84
	ds_bpermute_b32 v85, v84, v0
	s_waitcnt lgkmcnt(1)
	v_add_f32_e32 v80, v80, v82
	ds_bpermute_b32 v82, v84, v80
	s_waitcnt lgkmcnt(1)
	v_add_f32_e32 v0, v0, v85
	v_xor_b32_e32 v85, 8, v230
	v_cmp_lt_i32_e32 vcc, v85, v81
	s_waitcnt lgkmcnt(0)
	v_add_f32_e32 v80, v80, v82
	v_cndmask_b32_e32 v85, v230, v85, vcc
	v_lshlrev_b32_e32 v85, 2, v85
	ds_bpermute_b32 v86, v85, v0
	ds_bpermute_b32 v82, v85, v80
	s_waitcnt lgkmcnt(1)
	v_add_f32_e32 v0, v0, v86
	v_xor_b32_e32 v86, 16, v230
	v_cmp_lt_i32_e32 vcc, v86, v81
	s_waitcnt lgkmcnt(0)
	v_add_f32_e32 v80, v80, v82
	v_cndmask_b32_e32 v86, v230, v86, vcc
	v_lshlrev_b32_e32 v86, 2, v86
	ds_bpermute_b32 v87, v86, v0
	ds_bpermute_b32 v82, v86, v80
	s_waitcnt lgkmcnt(1)
	v_add_f32_e32 v0, v0, v87
	v_xor_b32_e32 v87, 32, v230
	v_cmp_lt_i32_e32 vcc, v87, v81
	s_waitcnt lgkmcnt(0)
	v_add_f32_e32 v80, v80, v82
	v_cndmask_b32_e32 v81, v230, v87, vcc
	v_lshlrev_b32_e32 v81, 2, v81
	ds_bpermute_b32 v87, v81, v0
	ds_bpermute_b32 v81, v81, v80
	s_waitcnt lgkmcnt(1)
	v_add_f32_e32 v0, v0, v87
	v_fmamk_f32 v0, v0, 0x3a800000, v227
	v_cmp_gt_f32_e32 vcc, s7, v0
	v_mul_f32_e32 v87, 0x4f800000, v0
	s_waitcnt lgkmcnt(0)
	v_add_f32_e32 v80, v80, v81
	v_cndmask_b32_e32 v0, v0, v87, vcc
	v_sqrt_f32_e32 v87, v0
	v_fmamk_f32 v80, v80, 0x3a800000, v227
	v_mul_f32_e32 v81, 0x4f800000, v80
	v_add_u32_e32 v88, -1, v87
	v_fma_f32 v89, -v88, v87, v0
	v_cmp_ge_f32_e64 s[40:41], 0, v89
	v_add_u32_e32 v89, 1, v87
	s_nop 0
	v_cndmask_b32_e64 v88, v87, v88, s[40:41]
	v_fma_f32 v87, -v89, v87, v0
	v_cmp_lt_f32_e64 s[40:41], 0, v87
	s_nop 1
	v_cndmask_b32_e64 v87, v88, v89, s[40:41]
	v_mul_f32_e32 v88, 0x37800000, v87
	v_cndmask_b32_e32 v87, v87, v88, vcc
	v_cmp_class_f32_e32 vcc, v0, v228
	s_nop 1
	v_cndmask_b32_e32 v0, v87, v0, vcc
	v_div_scale_f32 v87, s[40:41], v0, v0, 1.0
	v_rcp_f32_e32 v88, v87
	s_nop 0
	v_fma_f32 v89, -v87, v88, 1.0
	v_fmac_f32_e32 v88, v89, v88
	v_div_scale_f32 v89, vcc, 1.0, v0, 1.0
	v_mul_f32_e32 v90, v89, v88
	v_fma_f32 v91, -v87, v90, v89
	v_fmac_f32_e32 v90, v91, v88
	v_fma_f32 v87, -v87, v90, v89
	v_div_fmas_f32 v87, v87, v88, v90
	v_cmp_gt_f32_e32 vcc, s7, v80
	v_div_fixup_f32 v0, v87, v0, 1.0
	v_mul_f32_e32 v78, v78, v0
	v_cndmask_b32_e32 v80, v80, v81, vcc
	v_sqrt_f32_e32 v81, v80
	v_mul_f32_e32 v79, v79, v0
	v_mul_f32_e32 v78, v30, v78
	v_mul_f32_e32 v79, v31, v79
	v_add_u32_e32 v82, -1, v81
	v_fma_f32 v83, -v82, v81, v80
	v_cmp_ge_f32_e64 s[40:41], 0, v83
	v_add_u32_e32 v83, 1, v81
	v_mul_f32_e32 v76, v76, v0
	v_cndmask_b32_e64 v82, v81, v82, s[40:41]
	v_fma_f32 v81, -v83, v81, v80
	v_cmp_lt_f32_e64 s[40:41], 0, v81
	v_mul_f32_e32 v77, v77, v0
	v_cvt_pk_bf16_f32 v78, v78, v79
	v_mul_f32_e32 v76, v32, v76
	v_cndmask_b32_e64 v81, v82, v83, s[40:41]
	v_mul_f32_e32 v82, 0x37800000, v81
	v_cndmask_b32_e32 v81, v81, v82, vcc
	v_cmp_class_f32_e32 vcc, v80, v228
	v_mul_f32_e32 v77, v33, v77
	v_cvt_pk_bf16_f32 v79, v76, v77
	s_nop 0
	v_cndmask_b32_e32 v80, v81, v80, vcc
	v_div_scale_f32 v81, s[40:41], v80, v80, 1.0
	v_rcp_f32_e32 v82, v81
	s_nop 0
	v_fma_f32 v83, -v81, v82, 1.0
	v_fmac_f32_e32 v82, v83, v82
	v_div_scale_f32 v83, vcc, 1.0, v80, 1.0
	v_mul_f32_e32 v84, v83, v82
	v_fma_f32 v85, -v81, v84, v83
	v_fmac_f32_e32 v84, v85, v82
	v_fma_f32 v81, -v81, v84, v83
	v_div_fmas_f32 v81, v81, v82, v84
	v_div_fixup_f32 v82, v81, v80, 1.0
	v_mul_f32_e32 v74, v74, v82
	v_mul_f32_e32 v75, v75, v82
	v_mul_f32_e32 v72, v72, v82
	v_mul_f32_e32 v74, v30, v74
	v_mul_f32_e32 v75, v31, v75
	v_mul_f32_e32 v72, v32, v72
	v_mul_f32_e32 v73, v73, v82
	v_cvt_pk_bf16_f32 v74, v74, v75
	v_mul_f32_e32 v73, v33, v73
	v_cvt_pk_bf16_f32 v75, v72, v73
	v_add_co_u32_e32 v72, vcc, 0x3000000, v70
	v_lshl_add_u64 v[80:81], s[42:43], 1, v[64:65]
	s_nop 0
	v_addc_co_u32_e32 v73, vcc, 0, v71, vcc
	s_and_b64 vcc, exec, s[38:39]
	global_store_dwordx2 v[72:73], v[78:79], off sc1
	s_cbranch_vccnz .LBB0_797
	global_store_dwordx2 v[80:81], v[74:75], off sc1
.LBB0_797:
	v_mul_f32_e32 v54, v54, v0
	v_mul_f32_e32 v55, v55, v0
	v_mul_f32_e32 v54, v22, v54
	v_mul_f32_e32 v55, v23, v55
	v_cvt_pk_bf16_f32 v54, v54, v55
	v_mul_f32_e32 v55, v56, v0
	v_mul_f32_e32 v50, v50, v82
	v_mul_f32_e32 v51, v51, v82
	v_mul_f32_e32 v55, v24, v55
	v_mul_f32_e32 v56, v57, v0
	v_mul_f32_e32 v50, v22, v50
	v_mul_f32_e32 v51, v23, v51
	v_mul_f32_e32 v56, v25, v56
	v_cvt_pk_bf16_f32 v55, v55, v56
	v_cvt_pk_bf16_f32 v50, v50, v51
	v_mul_f32_e32 v51, v52, v82
	v_mul_f32_e32 v52, v53, v82
	v_mul_f32_e32 v51, v24, v51
	v_mul_f32_e32 v52, v25, v52
	v_cvt_pk_bf16_f32 v51, v51, v52
	v_add_co_u32_e32 v52, vcc, 0x3000000, v70
	s_nop 1
	v_addc_co_u32_e32 v53, vcc, 0, v71, vcc
	s_and_b64 vcc, exec, s[38:39]
	global_store_dwordx2 v[52:53], v[54:55], off offset:512 sc1
	s_cbranch_vccnz .LBB0_799
	global_store_dwordx2 v[80:81], v[50:51], off offset:512 sc1
.LBB0_799:
	v_mul_f32_e32 v46, v46, v0
	v_mul_f32_e32 v47, v47, v0
	v_mul_f32_e32 v46, v18, v46
	v_mul_f32_e32 v47, v19, v47
	v_cvt_pk_bf16_f32 v46, v46, v47
	v_mul_f32_e32 v47, v48, v0
	v_mul_f32_e32 v42, v42, v82
	v_mul_f32_e32 v43, v43, v82
	v_mul_f32_e32 v47, v20, v47
	v_mul_f32_e32 v48, v49, v0
	v_mul_f32_e32 v42, v18, v42
	v_mul_f32_e32 v43, v19, v43
	v_mul_f32_e32 v48, v21, v48
	v_cvt_pk_bf16_f32 v47, v47, v48
	v_cvt_pk_bf16_f32 v42, v42, v43
	v_mul_f32_e32 v43, v44, v82
	v_mul_f32_e32 v44, v45, v82
	v_mul_f32_e32 v43, v20, v43
	v_mul_f32_e32 v44, v21, v44
	v_cvt_pk_bf16_f32 v43, v43, v44
	v_add_co_u32_e32 v44, vcc, 0x3000000, v70
	s_nop 1
	v_addc_co_u32_e32 v45, vcc, 0, v71, vcc
	s_and_b64 vcc, exec, s[38:39]
	global_store_dwordx2 v[44:45], v[46:47], off offset:1024 sc1
	s_cbranch_vccnz .LBB0_801
	global_store_dwordx2 v[80:81], v[42:43], off offset:1024 sc1
.LBB0_801:
	v_mul_f32_e32 v38, v38, v0
	v_mul_f32_e32 v39, v39, v0
	v_mul_f32_e32 v38, v26, v38
	v_mul_f32_e32 v39, v27, v39
	v_cvt_pk_bf16_f32 v38, v38, v39
	v_mul_f32_e32 v39, v40, v0
	v_mul_f32_e32 v0, v41, v0
	v_mul_f32_e32 v39, v28, v39
	v_mul_f32_e32 v0, v29, v0
	v_cvt_pk_bf16_f32 v39, v39, v0
	v_mul_f32_e32 v0, v34, v82
	v_mul_f32_e32 v34, v35, v82
	v_mul_f32_e32 v0, v26, v0
	v_mul_f32_e32 v34, v27, v34
	v_cvt_pk_bf16_f32 v34, v0, v34
	v_mul_f32_e32 v0, v36, v82
	v_add_co_u32_e32 v36, vcc, 0x3000000, v70
	v_mul_f32_e32 v35, v37, v82
	s_nop 0
	v_addc_co_u32_e32 v37, vcc, 0, v71, vcc
	v_mul_f32_e32 v35, v29, v35
	s_and_b64 vcc, exec, s[38:39]
	v_mul_f32_e32 v0, v28, v0
	v_cvt_pk_bf16_f32 v35, v0, v35
	global_store_dwordx2 v[36:37], v[38:39], off offset:1536 sc1
	s_cbranch_vccnz .LBB0_786
	global_store_dwordx2 v[80:81], v[34:35], off offset:1536 sc1
	s_branch .LBB0_786

.LBB0_836:
	s_andn2_saveexec_b64 s[8:9], s[28:29]
	s_cbranch_execz .LBB0_105
	s_mov_b64 s[28:29], exec
	s_waitcnt lgkmcnt(0)
	s_waitcnt vmcnt(0)
	v_mbcnt_lo_u32_b32 v0, s28, 0
	v_mbcnt_hi_u32_b32 v0, s29, v0
	v_cmp_eq_u32_e32 vcc, 0, v0
	s_and_saveexec_b64 s[38:39], vcc
	s_cbranch_execz .LBB0_839
	s_bcnt1_i32_b64 s8, s[28:29]
	v_mov_b32_e32 v3, s8
	v_readlane_b32 s8, v241, 13
	v_readlane_b32 s9, v241, 14
	s_nop 4
	global_atomic_add v3, v1, v3, s[8:9] sc0
